# Swiglu epilogue: the 4 wc-waves of a row group each compute 2 of 8 rstd vectors (same instruction sequence, bit-identical) and share via LDS + one barrier; on top of stick-breaking exact early exit
# speedup vs baseline: 1.2187x; 1.0205x over previous
; #define GAS __attribute__((address_space(1)))
; template <int LD, int S0, int NS>
; __device__ __forceinline__ void rows_rstd(const float* st, int row0, int fq, float inv_n, float (&r)[2][4]) {
; #pragma unroll
;     for (int ai = 0; ai < 2; ++ai)
; #pragma unroll
;         for (int m = 0; m < 4; ++m) {
;             const GAS float* p = (const GAS float*)st + (size_t)(row0 + ai * 128 + m * 16) * LD + S0;
;             float s = 0.f;
;             if (NS == 32) { const f32x4 a = *(const GAS f32x4*)(p + fq * 8), b = *(const GAS f32x4*)(p + fq * 8 + 4); s = (a.x + a.y) + (a.z + a.w) + (b.x + b.y) + (b.z + b.w); }
;             else { if (fq * 4 < NS) { const f32x4 a = *(const GAS f32x4*)(p + fq * 4); s = (a.x + a.y) + (a.z + a.w); } }
;             s += __shfl_xor(s, 16); s += __shfl_xor(s, 32);
;             r[ai][m] = 1.0f / sqrtf(s * inv_n + EPS);
;         }
; }
;     __device__ __forceinline__ void operator()(const Acc& acc, const Unit& u, int wr, int wc, int fr, int fq) const {
;         asm volatile("" : "+v"(fr), "+v"(fq));
;         const int row0 = u.pm * 256 + wr * 64 + fr, col = u.pn * 128 + wc * 32 + 8 * fq;
;         float rs[2][4]; rows_rstd<32, 0, 32>(ssq, row0, fq, 1.0f / D, rs);
.LBB0_730:
	v_mov_b32_e32 v130, v165
	v_mov_b32_e32 v131, v171
	s_lshl_b32 s4, s8, 8
	s_add_i32 s4, s4, s46
	v_cmp_lt_i32_e32 vcc, v212, v218
	v_add_u32_e32 v148, s4, v130
	s_lshl_b32 s4, s9, 7
	v_lshlrev_b32_e32 v130, 3, v131
	v_cndmask_b32_e32 v132, v207, v212, vcc
	v_cmp_lt_i32_e32 vcc, v213, v218
	s_or_b32 s4, s4, s47
	v_ashrrev_i32_e32 v131, 31, v130
	v_lshlrev_b32_e32 v177, 2, v132
	v_cndmask_b32_e32 v132, v207, v213, vcc
	v_ashrrev_i32_e32 v149, 31, v148
	v_add_u32_e32 v150, s4, v130
	v_lshl_add_u64 v[130:131], v[130:131], 2, s[68:69]
	v_lshlrev_b32_e32 v151, 2, v132
	v_lshlrev_b64 v[132:133], 7, v[148:149]
	v_lshl_add_u64 v[136:137], v[130:131], 0, v[132:133]
	s_lshr_b32 s4, s47, 5
	s_and_b32 s5, s4, 1
	s_lshl_b32 s5, s5, 12
	s_lshr_b32 s4, s4, 1
	s_lshl_b32 s4, s4, 14
	s_add_i32 s4, s4, s5
	s_mov_b32 s5, 0
	v_lshl_add_u64 v[224:225], v[136:137], 0, s[4:5]
	global_load_dwordx4 v[132:135], v[224:225], off offset:16
	global_load_dwordx4 v[166:169], v[224:225], off
	global_load_dwordx4 v[228:231], v[224:225], off offset:2064
	global_load_dwordx4 v[232:235], v[224:225], off offset:2048
	s_waitcnt vmcnt(2)
	v_mov_b32_e32 v152, v134
	v_mov_b32_e32 v136, v167
	v_mov_b32_e32 v137, v168
	v_mov_b32_e32 v167, v169
	v_pk_add_f32 v[136:137], v[136:137], v[166:167]
	v_mov_b32_e32 v153, v132
	v_mov_b32_e32 v132, v135
	v_pk_add_f32 v[132:133], v[152:153], v[132:133]
	v_add_f32_e32 v134, v136, v137
	v_add_f32_e32 v133, v134, v133
	v_add_f32_e32 v132, v132, v133
	ds_bpermute_b32 v133, v177, v132
	s_waitcnt lgkmcnt(0)
	v_add_f32_e32 v132, v132, v133
	ds_bpermute_b32 v133, v151, v132
	s_waitcnt lgkmcnt(0)
	v_add_f32_e32 v132, v132, v133
	v_fmamk_f32 v132, v132, 0x3a000000, v205
	v_cmp_gt_f32_e32 vcc, s16, v132
	v_mul_f32_e32 v133, 0x4f800000, v132
	s_nop 0
	v_cndmask_b32_e32 v132, v132, v133, vcc
	v_sqrt_f32_e32 v133, v132
	s_nop 0
	v_add_u32_e32 v134, -1, v133
	v_fma_f32 v135, -v134, v133, v132
	v_cmp_ge_f32_e64 s[8:9], 0, v135
	v_add_u32_e32 v135, 1, v133
	s_nop 0
	v_cndmask_b32_e64 v134, v133, v134, s[8:9]
	v_fma_f32 v133, -v135, v133, v132
	v_cmp_lt_f32_e64 s[8:9], 0, v133
	s_nop 1
	v_cndmask_b32_e64 v133, v134, v135, s[8:9]
	v_mul_f32_e32 v134, 0x37800000, v133
	v_cndmask_b32_e32 v133, v133, v134, vcc
	v_cmp_class_f32_e32 vcc, v132, v206
	s_nop 1
	v_cndmask_b32_e32 v132, v133, v132, vcc
	v_div_scale_f32 v133, s[4:5], v132, v132, 1.0
	v_rcp_f32_e32 v134, v133
	s_nop 0
	v_fma_f32 v135, -v133, v134, 1.0
	v_fmac_f32_e32 v134, v135, v134
	v_div_scale_f32 v135, vcc, 1.0, v132, 1.0
	v_mul_f32_e32 v136, v135, v134
	v_fma_f32 v137, -v133, v136, v135
	v_fmac_f32_e32 v136, v137, v134
	v_fma_f32 v133, -v133, v136, v135
	v_div_fmas_f32 v133, v133, v134, v136
	v_div_fixup_f32 v236, v133, v132, 1.0
	s_waitcnt vmcnt(0)
	v_mov_b32_e32 v132, v228
	v_mov_b32_e32 v133, v229
	v_mov_b32_e32 v134, v230
	v_mov_b32_e32 v135, v231
	v_mov_b32_e32 v166, v232
	v_mov_b32_e32 v167, v233
	v_mov_b32_e32 v168, v234
	v_mov_b32_e32 v169, v235
	v_mov_b32_e32 v152, v134
	v_mov_b32_e32 v136, v167
	v_mov_b32_e32 v137, v168
	v_mov_b32_e32 v167, v169
	v_pk_add_f32 v[136:137], v[136:137], v[166:167]
	v_mov_b32_e32 v153, v132
	v_mov_b32_e32 v132, v135
	v_pk_add_f32 v[132:133], v[152:153], v[132:133]
	v_add_f32_e32 v134, v136, v137
	v_add_f32_e32 v133, v134, v133
	v_add_f32_e32 v132, v132, v133
	ds_bpermute_b32 v133, v177, v132
	s_waitcnt lgkmcnt(0)
	v_add_f32_e32 v132, v132, v133
	ds_bpermute_b32 v133, v151, v132
	s_waitcnt lgkmcnt(0)
	v_add_f32_e32 v132, v132, v133
	v_fmamk_f32 v132, v132, 0x3a000000, v205
	v_cmp_gt_f32_e32 vcc, s16, v132
	v_mul_f32_e32 v133, 0x4f800000, v132
	s_nop 0
	v_cndmask_b32_e32 v132, v132, v133, vcc
	v_sqrt_f32_e32 v133, v132
	s_nop 0
	v_add_u32_e32 v134, -1, v133
	v_fma_f32 v135, -v134, v133, v132
	v_cmp_ge_f32_e64 s[8:9], 0, v135
	v_add_u32_e32 v135, 1, v133
	s_nop 0
	v_cndmask_b32_e64 v134, v133, v134, s[8:9]
	v_fma_f32 v133, -v135, v133, v132
	v_cmp_lt_f32_e64 s[8:9], 0, v133
	s_nop 1
	v_cndmask_b32_e64 v133, v134, v135, s[8:9]
	v_mul_f32_e32 v134, 0x37800000, v133
	v_cndmask_b32_e32 v133, v133, v134, vcc
	v_cmp_class_f32_e32 vcc, v132, v206
	s_nop 1
	v_cndmask_b32_e32 v132, v133, v132, vcc
	v_div_scale_f32 v133, s[4:5], v132, v132, 1.0
	v_rcp_f32_e32 v134, v133
	s_nop 0
	v_fma_f32 v135, -v133, v134, 1.0
	v_fmac_f32_e32 v134, v135, v134
	v_div_scale_f32 v135, vcc, 1.0, v132, 1.0
	v_mul_f32_e32 v136, v135, v134
	v_fma_f32 v137, -v133, v136, v135
	v_fmac_f32_e32 v136, v137, v134
	v_fma_f32 v133, -v133, v136, v135
	v_div_fmas_f32 v133, v133, v134, v136
	v_div_fixup_f32 v237, v133, v132, 1.0
	s_lshl_b32 s4, s46, 3
	s_lshl_b32 s5, s47, 2
	s_add_i32 s4, s4, 139392
	s_add_i32 s5, s5, s4
	v_lshl_add_u32 v238, v165, 2, s5
	v_lshl_add_u32 v239, v165, 2, s4
	ds_write_b32 v238, v236
	ds_write_b32 v238, v237 offset:64
	s_waitcnt lgkmcnt(0)
	s_barrier
; #define GAS __attribute__((address_space(1)))
; __device__ __forceinline__ u32x4 pack8(const float* v) { u32x4 w; w.x = cvt_pk_bf16(v[0], v[1]); w.y = cvt_pk_bf16(v[2], v[3]); w.z = cvt_pk_bf16(v[4], v[5]); w.w = cvt_pk_bf16(v[6], v[7]); return w; }
;     __device__ __forceinline__ void operator()(const Acc& acc, const Unit& u, int wr, int wc, int fr, int fq) const {
;     ...
;         float rs[2][4]; rows_rstd<32, 0, 32>(ssq, row0, fq, 1.0f / D, rs);
; #pragma unroll
;         for (int ai = 0; ai < 2; ++ai)
; #pragma unroll
;             for (int m = 0; m < 4; ++m) { const float r = rs[ai][m]; float o[8];
; #pragma unroll
;                 for (int n = 0; n < 2; ++n)
; #pragma unroll
;                     for (int j = 0; j < 4; ++j) { const float g = acc[ai][0][m][n][j] * r, up = acc[ai][1][m][n][j] * r;
;                         o[4 * n + j] = g * __builtin_amdgcn_rcpf(1.0f + __builtin_amdgcn_exp2f(-g * LOG2E)) * up; }
;                 *(GAS u32x4*)((GAS bf16_t*)act + (size_t)(row0 + ai * 128 + m * 16) * FF + col) = pack8(o); __builtin_amdgcn_sched_barrier(0); }
	ds_read_b32 v170, v239
	ds_read_b32 v172, v239 offset:64
	ds_read_b32 v174, v239 offset:128
	ds_read_b32 v176, v239 offset:192
	ds_read_b32 v180, v239 offset:256
	ds_read_b32 v184, v239 offset:320
	ds_read_b32 v188, v239 offset:384
	ds_read_b32 v130, v239 offset:448
	v_add_u32_e32 v152, 16, v148
	v_ashrrev_i32_e32 v153, 31, v152
	v_add_u32_e32 v166, 32, v148
	v_ashrrev_i32_e32 v167, 31, v166
	v_add_u32_e32 v168, 48, v148
	v_ashrrev_i32_e32 v169, 31, v168
	v_add_u32_e32 v178, 0x80, v148
	v_ashrrev_i32_e32 v179, 31, v178
	v_add_u32_e32 v182, 0x90, v148
	v_ashrrev_i32_e32 v183, 31, v182
	v_add_u32_e32 v186, 0xa0, v148
	v_ashrrev_i32_e32 v187, 31, v186
	v_add_u32_e32 v190, 0xb0, v148
	v_ashrrev_i32_e32 v191, 31, v190
	v_ashrrev_i32_e32 v151, 31, v150
	v_readlane_b32 s4, v254, 54
	v_readlane_b32 s5, v254, 55
	s_waitcnt lgkmcnt(0)
	v_mov_b32_e32 v132, v126
	v_mov_b32_e32 v133, v122
	v_pk_mul_f32 v[132:133], v[132:133], v[170:171] op_sel_hi:[1,0]
	v_mul_f32_e32 v122, 0xbfb8aa3b, v133
	v_exp_f32_e32 v122, v122
	s_nop 0
	v_add_f32_e32 v122, 1.0, v122
	v_rcp_f32_e32 v122, v122
	s_nop 0
	v_mul_f32_e32 v122, v133, v122
	v_mul_f32_e32 v126, v132, v122
	v_mov_b32_e32 v122, v127
	v_pk_mul_f32 v[122:123], v[122:123], v[170:171] op_sel_hi:[1,0]
	s_nop 0
	v_mul_f32_e32 v127, 0xbfb8aa3b, v123
	v_exp_f32_e32 v127, v127
	s_nop 0
	v_add_f32_e32 v127, 1.0, v127
	v_rcp_f32_e32 v127, v127
	s_nop 0
	v_mul_f32_e32 v123, v123, v127
	v_mul_f32_e32 v127, v122, v123
	v_mov_b32_e32 v122, v128
	v_mov_b32_e32 v123, v124
	v_pk_mul_f32 v[122:123], v[122:123], v[170:171] op_sel_hi:[1,0]
	s_nop 0
	v_mul_f32_e32 v124, 0xbfb8aa3b, v123
	v_exp_f32_e32 v124, v124
	s_nop 0
	v_add_f32_e32 v124, 1.0, v124
	v_rcp_f32_e32 v124, v124
	s_nop 0
	v_mul_f32_e32 v123, v123, v124
	v_mov_b32_e32 v124, v129
	v_mul_f32_e32 v128, v122, v123
	v_pk_mul_f32 v[122:123], v[124:125], v[170:171] op_sel_hi:[1,0]
	s_nop 0
	v_mul_f32_e32 v124, 0xbfb8aa3b, v123
	v_exp_f32_e32 v124, v124
	s_nop 0
	v_add_f32_e32 v124, 1.0, v124
	v_rcp_f32_e32 v124, v124
	s_nop 0
	v_mul_f32_e32 v123, v123, v124
	v_mul_f32_e32 v124, v122, v123
	v_mov_b32_e32 v122, v118
	v_mov_b32_e32 v123, v114
	v_pk_mul_f32 v[122:123], v[122:123], v[170:171] op_sel_hi:[1,0]
	s_nop 0
	v_mul_f32_e32 v114, 0xbfb8aa3b, v123
	v_exp_f32_e32 v114, v114
	s_nop 0
	v_add_f32_e32 v114, 1.0, v114
	v_rcp_f32_e32 v114, v114
	s_nop 0
	v_mul_f32_e32 v114, v123, v114
	v_mul_f32_e32 v122, v122, v114
	v_mov_b32_e32 v114, v119
	v_pk_mul_f32 v[114:115], v[114:115], v[170:171] op_sel_hi:[1,0]
	s_nop 0
	v_mul_f32_e32 v118, 0xbfb8aa3b, v115
	v_exp_f32_e32 v118, v118
	s_nop 0
	v_add_f32_e32 v118, 1.0, v118
	v_rcp_f32_e32 v118, v118
	s_nop 0
	v_mul_f32_e32 v115, v115, v118
	v_mul_f32_e32 v123, v114, v115
	v_mov_b32_e32 v114, v120
	v_mov_b32_e32 v115, v116
	v_pk_mul_f32 v[114:115], v[114:115], v[170:171] op_sel_hi:[1,0]
	v_cvt_pk_bf16_f32 v118, v126, v127
	v_cvt_pk_bf16_f32 v119, v128, v124
	v_cvt_pk_bf16_f32 v120, v122, v123
	s_nop 0
	v_mul_f32_e32 v116, 0xbfb8aa3b, v115
	v_exp_f32_e32 v116, v116
	s_nop 0
	v_add_f32_e32 v116, 1.0, v116
	v_rcp_f32_e32 v116, v116
	s_nop 0
	v_mul_f32_e32 v115, v115, v116
	v_mov_b32_e32 v116, v121
	v_mul_f32_e32 v125, v114, v115
	v_pk_mul_f32 v[114:115], v[116:117], v[170:171] op_sel_hi:[1,0]
	s_nop 0
	v_mul_f32_e32 v116, 0xbfb8aa3b, v115
	v_exp_f32_e32 v116, v116
	s_nop 0
	v_add_f32_e32 v116, 1.0, v116
	v_rcp_f32_e32 v116, v116
	s_nop 0
	v_mul_f32_e32 v115, v115, v116
	v_mul_f32_e32 v114, v114, v115
	v_cvt_pk_bf16_f32 v121, v125, v114
	v_mov_b64_e32 v[114:115], s[4:5]
	v_mad_i64_i32 v[122:123], s[4:5], v148, s30, v[114:115]
	v_lshlrev_b64 v[116:117], 1, v[150:151]
	v_lshl_add_u64 v[122:123], v[122:123], 0, v[116:117]
	global_store_dwordx4 v[122:123], v[118:121], off
	s_nop 1
	v_mov_b32_e32 v118, v110
	v_mov_b32_e32 v119, v106
	v_pk_mul_f32 v[118:119], v[118:119], v[172:173] op_sel_hi:[1,0]
	s_nop 0
	v_mul_f32_e32 v106, 0xbfb8aa3b, v119
	v_exp_f32_e32 v106, v106
	s_nop 0
	v_add_f32_e32 v106, 1.0, v106
	v_rcp_f32_e32 v106, v106
	s_nop 0
	v_mul_f32_e32 v106, v119, v106
	v_mul_f32_e32 v110, v118, v106
	v_mov_b32_e32 v106, v111
	v_pk_mul_f32 v[106:107], v[106:107], v[172:173] op_sel_hi:[1,0]
	s_nop 0
	v_mul_f32_e32 v111, 0xbfb8aa3b, v107
	v_exp_f32_e32 v111, v111
	s_nop 0
	v_add_f32_e32 v111, 1.0, v111
	v_rcp_f32_e32 v111, v111
	s_nop 0
	v_mul_f32_e32 v107, v107, v111
	v_mul_f32_e32 v111, v106, v107
	v_mov_b32_e32 v106, v112
	v_mov_b32_e32 v107, v108
	v_pk_mul_f32 v[106:107], v[106:107], v[172:173] op_sel_hi:[1,0]
	s_nop 0
	v_mul_f32_e32 v108, 0xbfb8aa3b, v107
	v_exp_f32_e32 v108, v108
	s_nop 0
	v_add_f32_e32 v108, 1.0, v108
	v_rcp_f32_e32 v108, v108
	s_nop 0
	v_mul_f32_e32 v107, v107, v108
	v_mov_b32_e32 v108, v113
	v_mul_f32_e32 v112, v106, v107
	v_pk_mul_f32 v[106:107], v[108:109], v[172:173] op_sel_hi:[1,0]
	s_nop 0
	v_mul_f32_e32 v108, 0xbfb8aa3b, v107
	v_exp_f32_e32 v108, v108
	s_nop 0
	v_add_f32_e32 v108, 1.0, v108
	v_rcp_f32_e32 v108, v108
	s_nop 0
	v_mul_f32_e32 v107, v107, v108
	v_mul_f32_e32 v108, v106, v107
	v_mov_b32_e32 v106, v102
	v_mov_b32_e32 v107, v98
	v_pk_mul_f32 v[106:107], v[106:107], v[172:173] op_sel_hi:[1,0]
	s_nop 0
	v_mul_f32_e32 v98, 0xbfb8aa3b, v107
	v_exp_f32_e32 v98, v98
	s_nop 0
	v_add_f32_e32 v98, 1.0, v98
	v_rcp_f32_e32 v98, v98
	s_nop 0
	v_mul_f32_e32 v98, v107, v98
	v_mul_f32_e32 v102, v106, v98
	v_mov_b32_e32 v98, v103
	v_pk_mul_f32 v[98:99], v[98:99], v[172:173] op_sel_hi:[1,0]
	s_nop 0
	v_mul_f32_e32 v103, 0xbfb8aa3b, v99
	v_exp_f32_e32 v103, v103
	s_nop 0
	v_add_f32_e32 v103, 1.0, v103
	v_rcp_f32_e32 v103, v103
	s_nop 0
	v_mul_f32_e32 v99, v99, v103
	v_mul_f32_e32 v103, v98, v99
	v_mov_b32_e32 v98, v104
; #define GAS __attribute__((address_space(1)))
; __device__ __forceinline__ u32x4 pack8(const float* v) { u32x4 w; w.x = cvt_pk_bf16(v[0], v[1]); w.y = cvt_pk_bf16(v[2], v[3]); w.z = cvt_pk_bf16(v[4], v[5]); w.w = cvt_pk_bf16(v[6], v[7]); return w; }
;     __device__ __forceinline__ void operator()(const Acc& acc, const Unit& u, int wr, int wc, int fr, int fq) const {
;     ...
;             for (int m = 0; m < 4; ++m) { const float r = rs[ai][m]; float o[8];
; #pragma unroll
;                 for (int n = 0; n < 2; ++n)
; #pragma unroll
;                     for (int j = 0; j < 4; ++j) { const float g = acc[ai][0][m][n][j] * r, up = acc[ai][1][m][n][j] * r;
;                         o[4 * n + j] = g * __builtin_amdgcn_rcpf(1.0f + __builtin_amdgcn_exp2f(-g * LOG2E)) * up; }
;                 *(GAS u32x4*)((GAS bf16_t*)act + (size_t)(row0 + ai * 128 + m * 16) * FF + col) = pack8(o); __builtin_amdgcn_sched_barrier(0); }
	v_mov_b32_e32 v99, v100
	v_pk_mul_f32 v[98:99], v[98:99], v[172:173] op_sel_hi:[1,0]
	s_nop 0
	v_mul_f32_e32 v100, 0xbfb8aa3b, v99
	v_exp_f32_e32 v100, v100
	s_nop 0
	v_add_f32_e32 v100, 1.0, v100
	v_rcp_f32_e32 v100, v100
	s_nop 0
	v_mul_f32_e32 v99, v99, v100
	v_mov_b32_e32 v100, v105
	v_mul_f32_e32 v104, v98, v99
	v_pk_mul_f32 v[98:99], v[100:101], v[172:173] op_sel_hi:[1,0]
	s_nop 0
	v_mul_f32_e32 v100, 0xbfb8aa3b, v99
	v_exp_f32_e32 v100, v100
	s_nop 0
	v_add_f32_e32 v100, 1.0, v100
	v_rcp_f32_e32 v100, v100
	s_nop 0
	v_mul_f32_e32 v99, v99, v100
	v_mul_f32_e32 v101, v98, v99
	v_cvt_pk_bf16_f32 v98, v110, v111
	v_cvt_pk_bf16_f32 v99, v112, v108
	v_cvt_pk_bf16_f32 v100, v102, v103
	v_mad_i64_i32 v[102:103], s[4:5], v152, s30, v[114:115]
	v_lshl_add_u64 v[102:103], v[102:103], 0, v[116:117]
	v_cvt_pk_bf16_f32 v101, v104, v101
	global_store_dwordx4 v[102:103], v[98:101], off
	s_nop 1
	v_mov_b32_e32 v98, v94
	v_mov_b32_e32 v99, v90
	v_pk_mul_f32 v[98:99], v[98:99], v[174:175] op_sel_hi:[1,0]
	s_nop 0
	v_mul_f32_e32 v90, 0xbfb8aa3b, v99
	v_exp_f32_e32 v90, v90
	s_nop 0
	v_add_f32_e32 v90, 1.0, v90
	v_rcp_f32_e32 v90, v90
	s_nop 0
	v_mul_f32_e32 v90, v99, v90
	v_mul_f32_e32 v94, v98, v90
	v_mov_b32_e32 v90, v95
	v_pk_mul_f32 v[90:91], v[90:91], v[174:175] op_sel_hi:[1,0]
	s_nop 0
	v_mul_f32_e32 v95, 0xbfb8aa3b, v91
	v_exp_f32_e32 v95, v95
	s_nop 0
	v_add_f32_e32 v95, 1.0, v95
	v_rcp_f32_e32 v95, v95
	s_nop 0
	v_mul_f32_e32 v91, v91, v95
	v_mul_f32_e32 v95, v90, v91
	v_mov_b32_e32 v90, v96
	v_mov_b32_e32 v91, v92
	v_pk_mul_f32 v[90:91], v[90:91], v[174:175] op_sel_hi:[1,0]
	s_nop 0
	v_mul_f32_e32 v92, 0xbfb8aa3b, v91
	v_exp_f32_e32 v92, v92
	s_nop 0
	v_add_f32_e32 v92, 1.0, v92
	v_rcp_f32_e32 v92, v92
	s_nop 0
	v_mul_f32_e32 v91, v91, v92
	v_mov_b32_e32 v92, v97
	v_mul_f32_e32 v96, v90, v91
	v_pk_mul_f32 v[90:91], v[92:93], v[174:175] op_sel_hi:[1,0]
	s_nop 0
	v_mul_f32_e32 v92, 0xbfb8aa3b, v91
	v_exp_f32_e32 v92, v92
	s_nop 0
	v_add_f32_e32 v92, 1.0, v92
	v_rcp_f32_e32 v92, v92
	s_nop 0
	v_mul_f32_e32 v91, v91, v92
	v_mul_f32_e32 v92, v90, v91
	v_mov_b32_e32 v90, v86
	v_mov_b32_e32 v91, v82
	v_pk_mul_f32 v[90:91], v[90:91], v[174:175] op_sel_hi:[1,0]
	s_nop 0
	v_mul_f32_e32 v82, 0xbfb8aa3b, v91
	v_exp_f32_e32 v82, v82
	s_nop 0
	v_add_f32_e32 v82, 1.0, v82
	v_rcp_f32_e32 v82, v82
	s_nop 0
	v_mul_f32_e32 v82, v91, v82
	v_mul_f32_e32 v86, v90, v82
	v_mov_b32_e32 v82, v87
	v_pk_mul_f32 v[82:83], v[82:83], v[174:175] op_sel_hi:[1,0]
	s_nop 0
	v_mul_f32_e32 v87, 0xbfb8aa3b, v83
	v_exp_f32_e32 v87, v87
	s_nop 0
	v_add_f32_e32 v87, 1.0, v87
	v_rcp_f32_e32 v87, v87
	s_nop 0
	v_mul_f32_e32 v83, v83, v87
	v_mul_f32_e32 v87, v82, v83
	v_mov_b32_e32 v82, v88
	v_mov_b32_e32 v83, v84
	v_pk_mul_f32 v[82:83], v[82:83], v[174:175] op_sel_hi:[1,0]
	s_nop 0
	v_mul_f32_e32 v84, 0xbfb8aa3b, v83
	v_exp_f32_e32 v84, v84
	s_nop 0
	v_add_f32_e32 v84, 1.0, v84
	v_rcp_f32_e32 v84, v84
	s_nop 0
	v_mul_f32_e32 v83, v83, v84
	v_mov_b32_e32 v84, v89
	v_mul_f32_e32 v88, v82, v83
	v_pk_mul_f32 v[82:83], v[84:85], v[174:175] op_sel_hi:[1,0]
	s_nop 0
	v_mul_f32_e32 v84, 0xbfb8aa3b, v83
	v_exp_f32_e32 v84, v84
	s_nop 0
	v_add_f32_e32 v84, 1.0, v84
	v_rcp_f32_e32 v84, v84
	s_nop 0
	v_mul_f32_e32 v83, v83, v84
	v_mul_f32_e32 v85, v82, v83
	v_cvt_pk_bf16_f32 v82, v94, v95
	v_cvt_pk_bf16_f32 v83, v96, v92
	v_cvt_pk_bf16_f32 v84, v86, v87
	v_mad_i64_i32 v[86:87], s[4:5], v166, s30, v[114:115]
	v_lshl_add_u64 v[86:87], v[86:87], 0, v[116:117]
	v_cvt_pk_bf16_f32 v85, v88, v85
	global_store_dwordx4 v[86:87], v[82:85], off
	s_nop 1
	v_mov_b32_e32 v82, v78
	v_mov_b32_e32 v83, v74
	v_pk_mul_f32 v[82:83], v[82:83], v[176:177] op_sel_hi:[1,0]
	s_nop 0
	v_mul_f32_e32 v74, 0xbfb8aa3b, v83
	v_exp_f32_e32 v74, v74
	s_nop 0
	v_add_f32_e32 v74, 1.0, v74
	v_rcp_f32_e32 v74, v74
	s_nop 0
	v_mul_f32_e32 v74, v83, v74
	v_mul_f32_e32 v78, v82, v74
	v_mov_b32_e32 v74, v79
	v_pk_mul_f32 v[74:75], v[74:75], v[176:177] op_sel_hi:[1,0]
	s_nop 0
	v_mul_f32_e32 v79, 0xbfb8aa3b, v75
	v_exp_f32_e32 v79, v79
	s_nop 0
	v_add_f32_e32 v79, 1.0, v79
	v_rcp_f32_e32 v79, v79
	s_nop 0
	v_mul_f32_e32 v75, v75, v79
	v_mul_f32_e32 v79, v74, v75
	v_mov_b32_e32 v74, v80
	v_mov_b32_e32 v75, v76
	v_pk_mul_f32 v[74:75], v[74:75], v[176:177] op_sel_hi:[1,0]
	s_nop 0
	v_mul_f32_e32 v76, 0xbfb8aa3b, v75
	v_exp_f32_e32 v76, v76
	s_nop 0
	v_add_f32_e32 v76, 1.0, v76
	v_rcp_f32_e32 v76, v76
	s_nop 0
	v_mul_f32_e32 v75, v75, v76
	v_mov_b32_e32 v76, v81
	v_mul_f32_e32 v80, v74, v75
	v_pk_mul_f32 v[74:75], v[76:77], v[176:177] op_sel_hi:[1,0]
	s_nop 0
	v_mul_f32_e32 v76, 0xbfb8aa3b, v75
	v_exp_f32_e32 v76, v76
	s_nop 0
	v_add_f32_e32 v76, 1.0, v76
	v_rcp_f32_e32 v76, v76
	s_nop 0
	v_mul_f32_e32 v75, v75, v76
	v_mul_f32_e32 v76, v74, v75
	v_mov_b32_e32 v74, v70
	v_mov_b32_e32 v75, v66
	v_pk_mul_f32 v[74:75], v[74:75], v[176:177] op_sel_hi:[1,0]
	s_nop 0
	v_mul_f32_e32 v66, 0xbfb8aa3b, v75
	v_exp_f32_e32 v66, v66
	s_nop 0
	v_add_f32_e32 v66, 1.0, v66
	v_rcp_f32_e32 v66, v66
	s_nop 0
	v_mul_f32_e32 v66, v75, v66
	v_mul_f32_e32 v70, v74, v66
	v_mov_b32_e32 v66, v71
	v_pk_mul_f32 v[66:67], v[66:67], v[176:177] op_sel_hi:[1,0]
	s_nop 0
	v_mul_f32_e32 v71, 0xbfb8aa3b, v67
	v_exp_f32_e32 v71, v71
	s_nop 0
	v_add_f32_e32 v71, 1.0, v71
	v_rcp_f32_e32 v71, v71
	s_nop 0
	v_mul_f32_e32 v67, v67, v71
	v_mul_f32_e32 v71, v66, v67
	v_mov_b32_e32 v66, v72
	v_mov_b32_e32 v67, v68
	v_pk_mul_f32 v[66:67], v[66:67], v[176:177] op_sel_hi:[1,0]
	s_nop 0
	v_mul_f32_e32 v68, 0xbfb8aa3b, v67
	v_exp_f32_e32 v68, v68
	s_nop 0
	v_add_f32_e32 v68, 1.0, v68
	v_rcp_f32_e32 v68, v68
	s_nop 0
	v_mul_f32_e32 v67, v67, v68
	v_mov_b32_e32 v68, v73
	v_mul_f32_e32 v72, v66, v67
; #define GAS __attribute__((address_space(1)))
; __device__ __forceinline__ u32x4 pack8(const float* v) { u32x4 w; w.x = cvt_pk_bf16(v[0], v[1]); w.y = cvt_pk_bf16(v[2], v[3]); w.z = cvt_pk_bf16(v[4], v[5]); w.w = cvt_pk_bf16(v[6], v[7]); return w; }
;     __device__ __forceinline__ void operator()(const Acc& acc, const Unit& u, int wr, int wc, int fr, int fq) const {
;     ...
;             for (int m = 0; m < 4; ++m) { const float r = rs[ai][m]; float o[8];
; #pragma unroll
;                 for (int n = 0; n < 2; ++n)
; #pragma unroll
;                     for (int j = 0; j < 4; ++j) { const float g = acc[ai][0][m][n][j] * r, up = acc[ai][1][m][n][j] * r;
;                         o[4 * n + j] = g * __builtin_amdgcn_rcpf(1.0f + __builtin_amdgcn_exp2f(-g * LOG2E)) * up; }
;                 *(GAS u32x4*)((GAS bf16_t*)act + (size_t)(row0 + ai * 128 + m * 16) * FF + col) = pack8(o); __builtin_amdgcn_sched_barrier(0); }
	v_pk_mul_f32 v[66:67], v[68:69], v[176:177] op_sel_hi:[1,0]
	s_nop 0
	v_mul_f32_e32 v68, 0xbfb8aa3b, v67
	v_exp_f32_e32 v68, v68
	s_nop 0
	v_add_f32_e32 v68, 1.0, v68
	v_rcp_f32_e32 v68, v68
	s_nop 0
	v_mul_f32_e32 v67, v67, v68
	v_mul_f32_e32 v69, v66, v67
	v_cvt_pk_bf16_f32 v66, v78, v79
	v_cvt_pk_bf16_f32 v67, v80, v76
	v_cvt_pk_bf16_f32 v68, v70, v71
	v_mad_i64_i32 v[70:71], s[4:5], v168, s30, v[114:115]
	v_lshl_add_u64 v[70:71], v[70:71], 0, v[116:117]
	v_cvt_pk_bf16_f32 v69, v72, v69
	global_store_dwordx4 v[70:71], v[66:69], off
	s_nop 1
	v_mov_b32_e32 v66, v62
	v_mov_b32_e32 v67, v58
	v_pk_mul_f32 v[66:67], v[66:67], v[180:181] op_sel_hi:[1,0]
	s_nop 0
	v_mul_f32_e32 v58, 0xbfb8aa3b, v67
	v_exp_f32_e32 v58, v58
	s_nop 0
	v_add_f32_e32 v58, 1.0, v58
	v_rcp_f32_e32 v58, v58
	s_nop 0
	v_mul_f32_e32 v58, v67, v58
	v_mul_f32_e32 v62, v66, v58
	v_mov_b32_e32 v58, v63
	v_pk_mul_f32 v[58:59], v[58:59], v[180:181] op_sel_hi:[1,0]
	s_nop 0
	v_mul_f32_e32 v63, 0xbfb8aa3b, v59
	v_exp_f32_e32 v63, v63
	s_nop 0
	v_add_f32_e32 v63, 1.0, v63
	v_rcp_f32_e32 v63, v63
	s_nop 0
	v_mul_f32_e32 v59, v59, v63
	v_mul_f32_e32 v63, v58, v59
	v_mov_b32_e32 v58, v64
	v_mov_b32_e32 v59, v60
	v_pk_mul_f32 v[58:59], v[58:59], v[180:181] op_sel_hi:[1,0]
	s_nop 0
	v_mul_f32_e32 v60, 0xbfb8aa3b, v59
	v_exp_f32_e32 v60, v60
	s_nop 0
	v_add_f32_e32 v60, 1.0, v60
	v_rcp_f32_e32 v60, v60
	s_nop 0
	v_mul_f32_e32 v59, v59, v60
	v_mov_b32_e32 v60, v65
	v_mul_f32_e32 v64, v58, v59
	v_pk_mul_f32 v[58:59], v[60:61], v[180:181] op_sel_hi:[1,0]
	s_nop 0
	v_mul_f32_e32 v60, 0xbfb8aa3b, v59
	v_exp_f32_e32 v60, v60
	s_nop 0
	v_add_f32_e32 v60, 1.0, v60
	v_rcp_f32_e32 v60, v60
	s_nop 0
	v_mul_f32_e32 v59, v59, v60
	v_mul_f32_e32 v60, v58, v59
	v_mov_b32_e32 v58, v54
	v_mov_b32_e32 v59, v50
	v_pk_mul_f32 v[58:59], v[58:59], v[180:181] op_sel_hi:[1,0]
	s_nop 0
	v_mul_f32_e32 v50, 0xbfb8aa3b, v59
	v_exp_f32_e32 v50, v50
	s_nop 0
	v_add_f32_e32 v50, 1.0, v50
	v_rcp_f32_e32 v50, v50
	s_nop 0
	v_mul_f32_e32 v50, v59, v50
	v_mul_f32_e32 v54, v58, v50
	v_mov_b32_e32 v50, v55
	v_pk_mul_f32 v[50:51], v[50:51], v[180:181] op_sel_hi:[1,0]
	s_nop 0
	v_mul_f32_e32 v55, 0xbfb8aa3b, v51
	v_exp_f32_e32 v55, v55
	s_nop 0
	v_add_f32_e32 v55, 1.0, v55
	v_rcp_f32_e32 v55, v55
	s_nop 0
	v_mul_f32_e32 v51, v51, v55
	v_mul_f32_e32 v55, v50, v51
	v_mov_b32_e32 v50, v56
	v_mov_b32_e32 v51, v52
	v_pk_mul_f32 v[50:51], v[50:51], v[180:181] op_sel_hi:[1,0]
	s_nop 0
	v_mul_f32_e32 v52, 0xbfb8aa3b, v51
	v_exp_f32_e32 v52, v52
	s_nop 0
	v_add_f32_e32 v52, 1.0, v52
	v_rcp_f32_e32 v52, v52
	s_nop 0
	v_mul_f32_e32 v51, v51, v52
	v_mov_b32_e32 v52, v57
	v_mul_f32_e32 v56, v50, v51
	v_pk_mul_f32 v[50:51], v[52:53], v[180:181] op_sel_hi:[1,0]
	s_nop 0
	v_mul_f32_e32 v52, 0xbfb8aa3b, v51
	v_exp_f32_e32 v52, v52
	s_nop 0
	v_add_f32_e32 v52, 1.0, v52
	v_rcp_f32_e32 v52, v52
	s_nop 0
	v_mul_f32_e32 v51, v51, v52
	v_mul_f32_e32 v53, v50, v51
	v_cvt_pk_bf16_f32 v50, v62, v63
	v_cvt_pk_bf16_f32 v51, v64, v60
	v_cvt_pk_bf16_f32 v52, v54, v55
	v_mad_i64_i32 v[54:55], s[4:5], v178, s30, v[114:115]
	v_lshl_add_u64 v[54:55], v[54:55], 0, v[116:117]
	v_cvt_pk_bf16_f32 v53, v56, v53
	global_store_dwordx4 v[54:55], v[50:53], off
	s_nop 1
	v_mov_b32_e32 v50, v46
	v_mov_b32_e32 v51, v42
	v_pk_mul_f32 v[50:51], v[50:51], v[184:185] op_sel_hi:[1,0]
	s_nop 0
	v_mul_f32_e32 v42, 0xbfb8aa3b, v51
	v_exp_f32_e32 v42, v42
	s_nop 0
	v_add_f32_e32 v42, 1.0, v42
	v_rcp_f32_e32 v42, v42
	s_nop 0
	v_mul_f32_e32 v42, v51, v42
	v_mul_f32_e32 v46, v50, v42
	v_mov_b32_e32 v42, v47
	v_pk_mul_f32 v[42:43], v[42:43], v[184:185] op_sel_hi:[1,0]
	s_nop 0
	v_mul_f32_e32 v47, 0xbfb8aa3b, v43
	v_exp_f32_e32 v47, v47
	s_nop 0
	v_add_f32_e32 v47, 1.0, v47
	v_rcp_f32_e32 v47, v47
	s_nop 0
	v_mul_f32_e32 v43, v43, v47
	v_mul_f32_e32 v47, v42, v43
	v_mov_b32_e32 v42, v48
	v_mov_b32_e32 v43, v44
	v_pk_mul_f32 v[42:43], v[42:43], v[184:185] op_sel_hi:[1,0]
	s_nop 0
	v_mul_f32_e32 v44, 0xbfb8aa3b, v43
	v_exp_f32_e32 v44, v44
	s_nop 0
	v_add_f32_e32 v44, 1.0, v44
	v_rcp_f32_e32 v44, v44
	s_nop 0
	v_mul_f32_e32 v43, v43, v44
	v_mov_b32_e32 v44, v49
	v_mul_f32_e32 v48, v42, v43
	v_pk_mul_f32 v[42:43], v[44:45], v[184:185] op_sel_hi:[1,0]
	s_nop 0
	v_mul_f32_e32 v44, 0xbfb8aa3b, v43
	v_exp_f32_e32 v44, v44
	s_nop 0
	v_add_f32_e32 v44, 1.0, v44
	v_rcp_f32_e32 v44, v44
	s_nop 0
	v_mul_f32_e32 v43, v43, v44
	v_mul_f32_e32 v44, v42, v43
	v_mov_b32_e32 v42, v38
	v_mov_b32_e32 v43, v34
	v_pk_mul_f32 v[42:43], v[42:43], v[184:185] op_sel_hi:[1,0]
	s_nop 0
	v_mul_f32_e32 v34, 0xbfb8aa3b, v43
	v_exp_f32_e32 v34, v34
	s_nop 0
	v_add_f32_e32 v34, 1.0, v34
	v_rcp_f32_e32 v34, v34
	s_nop 0
	v_mul_f32_e32 v34, v43, v34
	v_mul_f32_e32 v38, v42, v34
	v_mov_b32_e32 v34, v39
	v_pk_mul_f32 v[34:35], v[34:35], v[184:185] op_sel_hi:[1,0]
	s_nop 0
	v_mul_f32_e32 v39, 0xbfb8aa3b, v35
	v_exp_f32_e32 v39, v39
	s_nop 0
	v_add_f32_e32 v39, 1.0, v39
	v_rcp_f32_e32 v39, v39
	s_nop 0
	v_mul_f32_e32 v35, v35, v39
	v_mul_f32_e32 v39, v34, v35
	v_mov_b32_e32 v34, v40
	v_mov_b32_e32 v35, v36
	v_pk_mul_f32 v[34:35], v[34:35], v[184:185] op_sel_hi:[1,0]
	s_nop 0
	v_mul_f32_e32 v36, 0xbfb8aa3b, v35
	v_exp_f32_e32 v36, v36
	s_nop 0
	v_add_f32_e32 v36, 1.0, v36
	v_rcp_f32_e32 v36, v36
	s_nop 0
	v_mul_f32_e32 v35, v35, v36
	v_mov_b32_e32 v36, v41
	v_mul_f32_e32 v40, v34, v35
	v_pk_mul_f32 v[34:35], v[36:37], v[184:185] op_sel_hi:[1,0]
	s_nop 0
	v_mul_f32_e32 v36, 0xbfb8aa3b, v35
	v_exp_f32_e32 v36, v36
	s_nop 0
	v_add_f32_e32 v36, 1.0, v36
	v_rcp_f32_e32 v36, v36
	s_nop 0
	v_mul_f32_e32 v35, v35, v36
	v_mul_f32_e32 v37, v34, v35
	v_cvt_pk_bf16_f32 v34, v46, v47
; #define GAS __attribute__((address_space(1)))
; __device__ __forceinline__ u32x4 pack8(const float* v) { u32x4 w; w.x = cvt_pk_bf16(v[0], v[1]); w.y = cvt_pk_bf16(v[2], v[3]); w.z = cvt_pk_bf16(v[4], v[5]); w.w = cvt_pk_bf16(v[6], v[7]); return w; }
; #define PG8_BAR __builtin_amdgcn_s_barrier()
; template <class Epi>
; __device__ __forceinline__ void gemm_phase(LAS unsigned char* lds, const Gemm g, const StaticOrder& S, const Epi& E) {
;     ...
;         if (!has_next) break;
; #pragma unroll
;         for (int a = 0; a < 2; ++a)
; #pragma unroll
;             for (int b = 0; b < 2; ++b)
; #pragma unroll
;                 for (int m = 0; m < 4; ++m)
; #pragma unroll
;                     for (int n = 0; n < 2; ++n) acc[a][b][m][n] = (f32x4){0.f, 0.f, 0.f, 0.f};
;         cur = nxt; cA = nA; cB = nB; ++ui;
;         if (wr == 1) PG8_BAR;
;     __device__ __forceinline__ void operator()(const Acc& acc, const Unit& u, int wr, int wc, int fr, int fq) const {
;     ...
;             for (int m = 0; m < 4; ++m) { const float r = rs[ai][m]; float o[8];
; #pragma unroll
;                 for (int n = 0; n < 2; ++n)
; #pragma unroll
;                     for (int j = 0; j < 4; ++j) { const float g = acc[ai][0][m][n][j] * r, up = acc[ai][1][m][n][j] * r;
;                         o[4 * n + j] = g * __builtin_amdgcn_rcpf(1.0f + __builtin_amdgcn_exp2f(-g * LOG2E)) * up; }
;                 *(GAS u32x4*)((GAS bf16_t*)act + (size_t)(row0 + ai * 128 + m * 16) * FF + col) = pack8(o); __builtin_amdgcn_sched_barrier(0); }
	v_cvt_pk_bf16_f32 v35, v48, v44
	v_cvt_pk_bf16_f32 v36, v38, v39
	v_mad_i64_i32 v[38:39], s[4:5], v182, s30, v[114:115]
	v_lshl_add_u64 v[38:39], v[38:39], 0, v[116:117]
	v_cvt_pk_bf16_f32 v37, v40, v37
	global_store_dwordx4 v[38:39], v[34:37], off
	s_nop 1
	v_mov_b32_e32 v34, v30
	v_mov_b32_e32 v35, v26
	v_pk_mul_f32 v[34:35], v[34:35], v[188:189] op_sel_hi:[1,0]
	s_nop 0
	v_mul_f32_e32 v26, 0xbfb8aa3b, v35
	v_exp_f32_e32 v26, v26
	s_nop 0
	v_add_f32_e32 v26, 1.0, v26
	v_rcp_f32_e32 v26, v26
	s_nop 0
	v_mul_f32_e32 v26, v35, v26
	v_mul_f32_e32 v30, v34, v26
	v_mov_b32_e32 v26, v31
	v_pk_mul_f32 v[26:27], v[26:27], v[188:189] op_sel_hi:[1,0]
	s_nop 0
	v_mul_f32_e32 v31, 0xbfb8aa3b, v27
	v_exp_f32_e32 v31, v31
	s_nop 0
	v_add_f32_e32 v31, 1.0, v31
	v_rcp_f32_e32 v31, v31
	s_nop 0
	v_mul_f32_e32 v27, v27, v31
	v_mul_f32_e32 v31, v26, v27
	v_mov_b32_e32 v26, v32
	v_mov_b32_e32 v27, v28
	v_pk_mul_f32 v[26:27], v[26:27], v[188:189] op_sel_hi:[1,0]
	s_nop 0
	v_mul_f32_e32 v28, 0xbfb8aa3b, v27
	v_exp_f32_e32 v28, v28
	s_nop 0
	v_add_f32_e32 v28, 1.0, v28
	v_rcp_f32_e32 v28, v28
	s_nop 0
	v_mul_f32_e32 v27, v27, v28
	v_mov_b32_e32 v28, v33
	v_mul_f32_e32 v32, v26, v27
	v_pk_mul_f32 v[26:27], v[28:29], v[188:189] op_sel_hi:[1,0]
	s_nop 0
	v_mul_f32_e32 v28, 0xbfb8aa3b, v27
	v_exp_f32_e32 v28, v28
	s_nop 0
	v_add_f32_e32 v28, 1.0, v28
	v_rcp_f32_e32 v28, v28
	s_nop 0
	v_mul_f32_e32 v27, v27, v28
	v_mul_f32_e32 v28, v26, v27
	v_mov_b32_e32 v26, v22
	v_mov_b32_e32 v27, v18
	v_pk_mul_f32 v[26:27], v[26:27], v[188:189] op_sel_hi:[1,0]
	s_nop 0
	v_mul_f32_e32 v18, 0xbfb8aa3b, v27
	v_exp_f32_e32 v18, v18
	s_nop 0
	v_add_f32_e32 v18, 1.0, v18
	v_rcp_f32_e32 v18, v18
	s_nop 0
	v_mul_f32_e32 v18, v27, v18
	v_mul_f32_e32 v22, v26, v18
	v_mov_b32_e32 v18, v23
	v_pk_mul_f32 v[18:19], v[18:19], v[188:189] op_sel_hi:[1,0]
	s_nop 0
	v_mul_f32_e32 v23, 0xbfb8aa3b, v19
	v_exp_f32_e32 v23, v23
	s_nop 0
	v_add_f32_e32 v23, 1.0, v23
	v_rcp_f32_e32 v23, v23
	s_nop 0
	v_mul_f32_e32 v19, v19, v23
	v_mul_f32_e32 v23, v18, v19
	v_mov_b32_e32 v18, v24
	v_mov_b32_e32 v19, v20
	v_pk_mul_f32 v[18:19], v[18:19], v[188:189] op_sel_hi:[1,0]
	s_nop 0
	v_mul_f32_e32 v20, 0xbfb8aa3b, v19
	v_exp_f32_e32 v20, v20
	s_nop 0
	v_add_f32_e32 v20, 1.0, v20
	v_rcp_f32_e32 v20, v20
	s_nop 0
	v_mul_f32_e32 v19, v19, v20
	v_mov_b32_e32 v20, v25
	v_mul_f32_e32 v24, v18, v19
	v_pk_mul_f32 v[18:19], v[20:21], v[188:189] op_sel_hi:[1,0]
	s_nop 0
	v_mul_f32_e32 v20, 0xbfb8aa3b, v19
	v_exp_f32_e32 v20, v20
	s_nop 0
	v_add_f32_e32 v20, 1.0, v20
	v_rcp_f32_e32 v20, v20
	s_nop 0
	v_mul_f32_e32 v19, v19, v20
	v_mul_f32_e32 v21, v18, v19
	v_cvt_pk_bf16_f32 v18, v30, v31
	v_cvt_pk_bf16_f32 v19, v32, v28
	v_cvt_pk_bf16_f32 v20, v22, v23
	v_mad_i64_i32 v[22:23], s[4:5], v186, s30, v[114:115]
	v_lshl_add_u64 v[22:23], v[22:23], 0, v[116:117]
	v_cvt_pk_bf16_f32 v21, v24, v21
	global_store_dwordx4 v[22:23], v[18:21], off
	s_nop 1
	v_mov_b32_e32 v18, v14
	v_mov_b32_e32 v19, v10
	v_pk_mul_f32 v[18:19], v[18:19], v[130:131] op_sel_hi:[1,0]
	s_nop 0
	v_mul_f32_e32 v10, 0xbfb8aa3b, v19
	v_exp_f32_e32 v10, v10
	s_nop 0
	v_add_f32_e32 v10, 1.0, v10
	v_rcp_f32_e32 v10, v10
	s_nop 0
	v_mul_f32_e32 v10, v19, v10
	v_mul_f32_e32 v14, v18, v10
	v_mov_b32_e32 v10, v15
	v_pk_mul_f32 v[10:11], v[10:11], v[130:131] op_sel_hi:[1,0]
	s_nop 0
	v_mul_f32_e32 v15, 0xbfb8aa3b, v11
	v_exp_f32_e32 v15, v15
	s_nop 0
	v_add_f32_e32 v15, 1.0, v15
	v_rcp_f32_e32 v15, v15
	s_nop 0
	v_mul_f32_e32 v11, v11, v15
	v_mul_f32_e32 v15, v10, v11
	v_mov_b32_e32 v10, v16
	v_mov_b32_e32 v11, v12
	v_pk_mul_f32 v[10:11], v[10:11], v[130:131] op_sel_hi:[1,0]
	s_nop 0
	v_mul_f32_e32 v12, 0xbfb8aa3b, v11
	v_exp_f32_e32 v12, v12
	s_nop 0
	v_add_f32_e32 v12, 1.0, v12
	v_rcp_f32_e32 v12, v12
	s_nop 0
	v_mul_f32_e32 v11, v11, v12
	v_mov_b32_e32 v12, v17
	v_mul_f32_e32 v16, v10, v11
	v_pk_mul_f32 v[10:11], v[12:13], v[130:131] op_sel_hi:[1,0]
	s_nop 0
	v_mul_f32_e32 v12, 0xbfb8aa3b, v11
	v_exp_f32_e32 v12, v12
	s_nop 0
	v_add_f32_e32 v12, 1.0, v12
	v_rcp_f32_e32 v12, v12
	s_nop 0
	v_mul_f32_e32 v11, v11, v12
	v_mul_f32_e32 v12, v10, v11
	v_mov_b32_e32 v10, v2
	v_mov_b32_e32 v11, v6
	v_pk_mul_f32 v[10:11], v[10:11], v[130:131] op_sel_hi:[1,0]
	v_mov_b32_e32 v6, v3
	v_mul_f32_e32 v2, 0xbfb8aa3b, v11
	v_exp_f32_e32 v2, v2
	s_nop 0
	v_add_f32_e32 v2, 1.0, v2
	v_rcp_f32_e32 v2, v2
	s_nop 0
	v_mul_f32_e32 v2, v11, v2
	v_mul_f32_e32 v10, v10, v2
	v_pk_mul_f32 v[2:3], v[6:7], v[130:131] op_sel_hi:[1,0]
	s_nop 0
	v_mul_f32_e32 v6, 0xbfb8aa3b, v3
	v_exp_f32_e32 v6, v6
	s_nop 0
	v_add_f32_e32 v6, 1.0, v6
	v_rcp_f32_e32 v6, v6
	s_nop 0
	v_mul_f32_e32 v3, v3, v6
	v_mul_f32_e32 v6, v2, v3
	v_mov_b32_e32 v2, v4
	v_mov_b32_e32 v3, v8
	v_pk_mul_f32 v[2:3], v[2:3], v[130:131] op_sel_hi:[1,0]
	v_mov_b32_e32 v8, v5
	v_mul_f32_e32 v4, 0xbfb8aa3b, v3
	v_exp_f32_e32 v4, v4
	s_nop 0
	v_add_f32_e32 v4, 1.0, v4
	v_rcp_f32_e32 v4, v4
	s_nop 0
	v_mul_f32_e32 v3, v3, v4
	v_mul_f32_e32 v7, v2, v3
	v_pk_mul_f32 v[2:3], v[8:9], v[130:131] op_sel_hi:[1,0]
	s_nop 0
	v_mul_f32_e32 v4, 0xbfb8aa3b, v3
	v_exp_f32_e32 v4, v4
	s_nop 0
	v_add_f32_e32 v4, 1.0, v4
	v_rcp_f32_e32 v4, v4
	s_nop 0
	v_mul_f32_e32 v3, v3, v4
	v_mul_f32_e32 v5, v2, v3
	v_cvt_pk_bf16_f32 v2, v14, v15
	v_cvt_pk_bf16_f32 v3, v16, v12
	v_cvt_pk_bf16_f32 v4, v10, v6
	v_cvt_pk_bf16_f32 v5, v7, v5
	v_mad_i64_i32 v[6:7], s[4:5], v190, s30, v[114:115]
	v_lshl_add_u64 v[6:7], v[6:7], 0, v[116:117]
	global_store_dwordx4 v[6:7], v[2:5], off
	s_andn2_b64 vcc, exec, s[6:7]
	s_mov_b64 s[4:5], -1
	s_cbranch_vccnz .LBB0_722
	s_andn2_b64 vcc, exec, s[10:11]
	s_cbranch_vccnz .LBB0_721
	s_barrier
	s_branch .LBB0_721
